# v3 plus: GEMM accumulator zero-init hoisted above the first LDS-DMA wait
# baseline (speedup 1.0000x reference)
; DI int my_tid() { int t = threadIdx.x; asm volatile("" : "+v"(t)); return t; }
; #define RAW_BARRIER() do { asm volatile("s_waitcnt lgkmcnt(0)" ::: "memory"); __builtin_amdgcn_s_barrier(); } while (0)
; #define WAIT_VM(n) asm volatile("s_waitcnt vmcnt(" #n ")" ::: "memory")
; template <bool AF32>
; DI void gemm_main(const void* Ap, int lda, const short* Bp, int K, char* smem, f32x16 (&acc)[4][2]) {
;   const int tid = my_tid(), lane = tid & 63, w = tid >> 6, r = lane & 31, h = lane >> 5;
;   const int wm = w >> 2, wn = w & 3;
; #pragma unroll
;   for (int a = 0; a < 4; a++)
; #pragma unroll
;     for (int b = 0; b < 2; b++)
; #pragma unroll
;       for (int i = 0; i < 16; i++) acc[a][b][i] = 0.f;
;   const int lch = (lane & 3) ^ ((lane >> 4) & 3);
;   const short* ga = (const short*)Ap + (size_t)(w * 32 + (lane >> 2)) * lda + lch * 8;
;   const short* gb = Bp + (size_t)(w * 32 + (lane >> 2)) * K + lch * 8;
;   const size_t a16 = (size_t)16 * lda, b16 = (size_t)16 * K;
;   char* lbase = smem + w * 2048;
;     ...
;   const int x = (r >> 2) & 3;
;   const int off0 = ((h ^ x) << 4);
;   const int aoff = (wm * 128 + r) * 64, boff = GBOFF + (wn * 64 + r) * 64;
;   struct Frag { bf16x8 a[4], b0, b1; };
;     ...
;   const int nk = K >> 5;
;   Frag F0, F1;
;   GLDS(0, 0);
;   GLDS(1, 1);
;   GLDS(2, 2);
;   GLDS(3, 3);
;   WAIT_VM(12);
;   RAW_BARRIER();
.LBB0_13:
	s_mul_hi_i32 s6, s35, 0x78787879
	s_lshr_b32 s7, s6, 31
	s_ashr_i32 s6, s6, 4
	s_add_i32 s8, s6, s7
	s_mul_i32 s6, s8, 34
	s_sub_i32 s7, s35, s6
	s_ashr_i32 s6, s7, 1
	s_and_b32 s24, s7, 1
	s_ashr_i32 s7, s6, 31
	s_lshl_b64 s[22:23], s[6:7], 19
	s_add_u32 s28, s26, s22
	s_addc_u32 s29, s27, s23
	s_ashr_i32 s9, s8, 31
	s_lshl_b64 s[20:21], s[8:9], 20
	v_mov_b32_e32 v8, v196
	s_add_u32 s7, s30, s20
	s_addc_u32 s9, s34, s21
	s_waitcnt vmcnt(0)
	v_ashrrev_i32_e32 v7, 6, v8
	v_bfe_u32 v0, v8, 2, 4
	s_lshl_b32 s25, s24, 19
	v_lshrrev_b32_e32 v10, 4, v8
	v_lshl_or_b32 v0, v7, 5, v0
	s_add_u32 s36, s7, s25
	v_xor_b32_e32 v4, v10, v8
	v_ashrrev_i32_e32 v1, 31, v0
	s_addc_u32 s37, s9, 0
	v_bfe_u32 v9, v8, 5, 1
	v_lshlrev_b64 v[0:1], 11, v[0:1]
	v_lshlrev_b32_e32 v4, 4, v4
	v_lshlrev_b32_e32 v189, 11, v7
	v_lshrrev_b32_e32 v7, 2, v8
	v_lshl_add_u64 v[2:3], s[28:29], 0, v[0:1]
	v_and_b32_e32 v128, 48, v4
	v_lshl_add_u64 v[4:5], s[36:37], 0, v[0:1]
	v_bitop3_b32 v7, v9, v7, 3 bitop3:0x78
	v_and_b32_e32 v6, 31, v8
	v_lshl_add_u64 v[2:3], v[2:3], 0, v[128:129]
	v_lshl_add_u64 v[4:5], v[4:5], 0, v[128:129]
	v_lshlrev_b32_e32 v128, 4, v7
	v_lshrrev_b32_e32 v7, 1, v8
	v_and_or_b32 v6, v7, s65, v6
	v_readfirstlane_b32 s7, v189
	v_or_b32_e32 v9, 0x400, v189
	v_lshlrev_b32_e32 v186, 6, v6
	v_lshlrev_b32_e32 v6, 6, v8
	s_mov_b32 m0, s7
	s_mov_b64 s[28:29], 0x8000
	v_readfirstlane_b32 s7, v9
	v_and_b32_e32 v188, 0x37c0, v6
	global_load_lds_dwordx4 v[2:3], off
	v_lshl_add_u64 v[6:7], v[2:3], 0, s[28:29]
	s_mov_b32 m0, s7
	v_add_u32_e32 v9, 0x4400, v189
	global_load_lds_dwordx4 v[6:7], off
	v_add_u32_e32 v6, 0x4000, v189
	v_xor_b32_e32 v187, 32, v128
	v_readfirstlane_b32 s7, v6
	s_mov_b32 m0, s7
	v_readfirstlane_b32 s7, v9
	v_add_u32_e32 v9, 0x8000, v189
	global_load_lds_dwordx4 v[4:5], off
	v_lshl_add_u64 v[6:7], v[4:5], 0, s[28:29]
	s_mov_b32 m0, s7
	v_readfirstlane_b32 s7, v9
	v_add_u32_e32 v9, 0x8400, v189
	global_load_lds_dwordx4 v[6:7], off
	v_lshl_add_u64 v[6:7], v[2:3], 0, 64
	s_mov_b32 m0, s7
	v_readfirstlane_b32 s7, v9
	v_add_u32_e32 v9, 0xc000, v189
	global_load_lds_dwordx4 v[6:7], off
	v_lshl_add_u64 v[6:7], v[2:3], 0, s[66:67]
	s_mov_b32 m0, s7
	v_readfirstlane_b32 s7, v9
	v_add_u32_e32 v9, 0xc400, v189
	global_load_lds_dwordx4 v[6:7], off
	v_lshl_add_u64 v[6:7], v[4:5], 0, 64
	s_mov_b32 m0, s7
	v_readfirstlane_b32 s7, v9
	v_add_u32_e32 v9, 0x10000, v189
	global_load_lds_dwordx4 v[6:7], off
	v_lshl_add_u64 v[6:7], v[4:5], 0, s[66:67]
	s_mov_b32 m0, s7
	v_readfirstlane_b32 s7, v9
	v_add_u32_e32 v9, 0x10400, v189
	global_load_lds_dwordx4 v[6:7], off
	v_lshl_add_u64 v[6:7], v[2:3], 0, s[68:69]
	s_mov_b32 m0, s7
	v_readfirstlane_b32 s7, v9
	v_add_u32_e32 v9, 0x14000, v189
	global_load_lds_dwordx4 v[6:7], off
	v_lshl_add_u64 v[6:7], v[2:3], 0, s[70:71]
	s_mov_b32 m0, s7
	v_readfirstlane_b32 s7, v9
	v_add_u32_e32 v9, 0x14400, v189
	global_load_lds_dwordx4 v[6:7], off
	v_lshl_add_u64 v[6:7], v[4:5], 0, s[68:69]
	s_mov_b32 m0, s7
	v_readfirstlane_b32 s7, v9
	v_add_u32_e32 v9, 0x18000, v189
	global_load_lds_dwordx4 v[6:7], off
	v_lshl_add_u64 v[6:7], v[4:5], 0, s[70:71]
	s_mov_b32 m0, s7
	v_readfirstlane_b32 s7, v9
	global_load_lds_dwordx4 v[6:7], off
	v_lshl_add_u64 v[6:7], v[2:3], 0, s[72:73]
	s_mov_b32 m0, s7
	v_lshl_add_u64 v[2:3], v[2:3], 0, s[74:75]
	global_load_lds_dwordx4 v[6:7], off
	v_add_u32_e32 v6, 0x18400, v189
	s_nop 0
	v_readfirstlane_b32 s7, v6
	v_add_u32_e32 v6, 0x1c000, v189
	s_mov_b32 m0, s7
	v_readfirstlane_b32 s7, v6
	global_load_lds_dwordx4 v[2:3], off
	v_lshl_add_u64 v[2:3], v[4:5], 0, s[72:73]
	s_mov_b32 m0, s7
	s_nop 0
	global_load_lds_dwordx4 v[2:3], off
	v_lshl_add_u64 v[2:3], v[4:5], 0, s[74:75]
	v_add_u32_e32 v4, 0x1c400, v189
	s_nop 0
	v_readfirstlane_b32 s7, v4
	s_mov_b32 m0, s7
	s_and_b32 s7, s35, 1
	global_load_lds_dwordx4 v[2:3], off
	v_mov_b32_e32 v5, 0
	v_mov_b32_e32 v6, 0
	v_mov_b32_e32 v7, 0
	v_mov_b32_e32 v9, 0
	v_mov_b32_e32 v11, 0
	v_mov_b32_e32 v12, 0
	v_mov_b32_e32 v13, 0
	v_mov_b32_e32 v14, 0
	v_mov_b32_e32 v15, 0
	v_mov_b32_e32 v16, 0
	v_mov_b32_e32 v17, 0
	v_mov_b32_e32 v18, 0
	v_mov_b32_e32 v19, 0
	v_mov_b32_e32 v20, 0
	v_mov_b32_e32 v21, 0
	v_mov_b32_e32 v22, 0
	v_mov_b32_e32 v23, 0
	v_mov_b32_e32 v24, 0
	v_mov_b32_e32 v25, 0
	v_mov_b32_e32 v26, 0
	v_mov_b32_e32 v27, 0
	v_mov_b32_e32 v28, 0
	v_mov_b32_e32 v29, 0
	v_mov_b32_e32 v30, 0
	v_mov_b32_e32 v31, 0
	v_mov_b32_e32 v32, 0
	v_mov_b32_e32 v33, 0
	v_mov_b32_e32 v34, 0
	v_mov_b32_e32 v35, 0
	v_mov_b32_e32 v36, 0
	v_mov_b32_e32 v37, 0
	v_mov_b32_e32 v38, 0
	v_mov_b32_e32 v39, 0
	v_mov_b32_e32 v40, 0
	v_mov_b32_e32 v41, 0
	v_mov_b32_e32 v42, 0
	v_mov_b32_e32 v43, 0
	v_mov_b32_e32 v44, 0
	v_mov_b32_e32 v45, 0
	v_mov_b32_e32 v46, 0
	v_mov_b32_e32 v47, 0
	v_mov_b32_e32 v48, 0
	v_mov_b32_e32 v49, 0
	v_mov_b32_e32 v50, 0
	v_mov_b32_e32 v51, 0
	v_mov_b32_e32 v52, 0
	v_mov_b32_e32 v53, 0
	v_mov_b32_e32 v54, 0
	v_mov_b32_e32 v55, 0
	v_mov_b32_e32 v56, 0
	v_mov_b32_e32 v57, 0
	v_mov_b32_e32 v58, 0
	v_mov_b32_e32 v59, 0
	v_mov_b32_e32 v60, 0
	v_mov_b32_e32 v61, 0
	v_mov_b32_e32 v62, 0
	v_mov_b32_e32 v63, 0
	v_mov_b32_e32 v64, 0
	v_mov_b32_e32 v65, 0
	v_mov_b32_e32 v66, 0
	v_mov_b32_e32 v67, 0
	v_mov_b32_e32 v68, 0
	v_mov_b32_e32 v69, 0
	v_mov_b32_e32 v70, 0
	v_mov_b32_e32 v71, 0
	v_mov_b32_e32 v72, 0
	v_mov_b32_e32 v73, 0
	v_mov_b32_e32 v74, 0
	v_mov_b32_e32 v75, 0
	v_mov_b32_e32 v76, 0
	v_mov_b32_e32 v77, 0
	v_mov_b32_e32 v78, 0
	v_mov_b32_e32 v79, 0
	v_mov_b32_e32 v80, 0
	v_mov_b32_e32 v81, 0
	v_mov_b32_e32 v82, 0
	v_mov_b32_e32 v83, 0
	v_mov_b32_e32 v84, 0
	v_mov_b32_e32 v85, 0
	v_mov_b32_e32 v86, 0
	v_mov_b32_e32 v87, 0
	v_mov_b32_e32 v88, 0
	v_mov_b32_e32 v89, 0
	v_mov_b32_e32 v90, 0
	v_mov_b32_e32 v91, 0
	v_mov_b32_e32 v92, 0
	v_mov_b32_e32 v93, 0
	v_mov_b32_e32 v94, 0
	v_mov_b32_e32 v95, 0
	v_mov_b32_e32 v96, 0
	v_mov_b32_e32 v97, 0
	v_mov_b32_e32 v98, 0
	v_mov_b32_e32 v99, 0
	v_mov_b32_e32 v100, 0
	v_mov_b32_e32 v101, 0
	v_mov_b32_e32 v102, 0
	v_mov_b32_e32 v103, 0
	v_mov_b32_e32 v104, 0
	v_mov_b32_e32 v105, 0
	v_mov_b32_e32 v106, 0
	v_mov_b32_e32 v107, 0
	v_mov_b32_e32 v108, 0
	v_mov_b32_e32 v109, 0
	v_mov_b32_e32 v110, 0
	v_mov_b32_e32 v111, 0
	v_mov_b32_e32 v112, 0
	v_mov_b32_e32 v113, 0
	v_mov_b32_e32 v114, 0
	v_mov_b32_e32 v115, 0
	v_mov_b32_e32 v116, 0
	v_mov_b32_e32 v117, 0
	v_mov_b32_e32 v118, 0
	v_mov_b32_e32 v119, 0
	v_mov_b32_e32 v120, 0
	v_mov_b32_e32 v121, 0
	v_mov_b32_e32 v122, 0
	v_mov_b32_e32 v123, 0
	v_mov_b32_e32 v124, 0
	v_mov_b32_e32 v125, 0
	v_mov_b32_e32 v126, 0
	v_mov_b32_e32 v127, 0
	s_waitcnt vmcnt(12)
	v_or_b32_e32 v2, v186, v128
	s_waitcnt lgkmcnt(0)
	s_barrier
; #define RAW_BARRIER() do { asm volatile("s_waitcnt lgkmcnt(0)" ::: "memory"); __builtin_amdgcn_s_barrier(); } while (0)
; #define WAIT_VM(n) asm volatile("s_waitcnt vmcnt(" #n ")" ::: "memory")
; template <bool AF32>
; DI void gemm_main(const void* Ap, int lda, const short* Bp, int K, char* smem, f32x16 (&acc)[4][2]) {
;     ...
;   const int lch = (lane & 3) ^ ((lane >> 4) & 3);
;   const short* ga = (const short*)Ap + (size_t)(w * 32 + (lane >> 2)) * lda + lch * 8;
;   const short* gb = Bp + (size_t)(w * 32 + (lane >> 2)) * K + lch * 8;
;   const size_t a16 = (size_t)16 * lda, b16 = (size_t)16 * K;
;   char* lbase = smem + w * 2048;
;     ...
;   const int x = (r >> 2) & 3;
;   const int off0 = ((h ^ x) << 4);
;   const int aoff = (wm * 128 + r) * 64, boff = GBOFF + (wn * 64 + r) * 64;
;   struct Frag { bf16x8 a[4], b0, b1; };
;     ...
;   const int nk = K >> 5;
;   Frag F0, F1;
;   GLDS(0, 0);
;   GLDS(1, 1);
;   GLDS(2, 2);
;   GLDS(3, 3);
;   WAIT_VM(12);
;   RAW_BARRIER();
;   LOADF(F0, 0, 0);
	ds_read_b128 v[130:133], v2 offset:6144
	ds_read_b128 v[142:145], v2 offset:4096
	ds_read_b128 v[146:149], v2 offset:2048
	ds_read_b128 v[150:153], v2
	v_or_b32_e32 v2, v188, v128
	s_lshl_b32 s7, s7, 19
	ds_read_b128 v[134:137], v2 offset:18432
	ds_read_b128 v[138:141], v2 offset:16384
	v_bitop3_b32 v4, v10, 3, v8 bitop3:0x48
	s_or_b32 s20, s20, s7
	v_lshl_add_u64 v[2:3], s[22:23], 0, v[0:1]
	v_lshlrev_b32_e32 v4, 4, v4
	v_lshl_add_u64 v[0:1], s[20:21], 0, v[0:1]
	v_or_b32_e32 v0, v0, v4
	v_or_b32_e32 v2, v2, v4
	v_lshl_add_u64 v[180:181], s[16:17], 0, v[0:1]
	v_mov_b32_e32 v0, 0
	v_lshl_add_u64 v[178:179], s[16:17], 0, v[2:3]
	s_mov_b64 s[20:21], 0
	s_mov_b32 s7, 0
	v_mov_b32_e32 v1, v0
	v_mov_b32_e32 v2, v0
	v_mov_b32_e32 v3, v0
	v_mov_b32_e32 v4, v0
	v_mov_b32_e32 v8, v0
	v_mov_b32_e32 v10, v0

; DI int my_tid() { int t = threadIdx.x; asm volatile("" : "+v"(t)); return t; }
; #define RAW_BARRIER() do { asm volatile("s_waitcnt lgkmcnt(0)" ::: "memory"); __builtin_amdgcn_s_barrier(); } while (0)
; #define WAIT_VM(n) asm volatile("s_waitcnt vmcnt(" #n ")" ::: "memory")
; template <bool AF32>
; DI void gemm_main(const void* Ap, int lda, const short* Bp, int K, char* smem, f32x16 (&acc)[4][2]) {
;   const int tid = my_tid(), lane = tid & 63, w = tid >> 6, r = lane & 31, h = lane >> 5;
;   const int wm = w >> 2, wn = w & 3;
; #pragma unroll
;   for (int a = 0; a < 4; a++)
; #pragma unroll
;     for (int b = 0; b < 2; b++)
; #pragma unroll
;       for (int i = 0; i < 16; i++) acc[a][b][i] = 0.f;
;   const int lch = (lane & 3) ^ ((lane >> 4) & 3);
;   const short* ga = (const short*)Ap + (size_t)(w * 32 + (lane >> 2)) * lda + lch * 8;
;   const short* gb = Bp + (size_t)(w * 32 + (lane >> 2)) * K + lch * 8;
;   const size_t a16 = (size_t)16 * lda, b16 = (size_t)16 * K;
;   char* lbase = smem + w * 2048;
;     ...
;   const int x = (r >> 2) & 3;
;   const int off0 = ((h ^ x) << 4);
;   const int aoff = (wm * 128 + r) * 64, boff = GBOFF + (wn * 64 + r) * 64;
;   struct Frag { bf16x8 a[4], b0, b1; };
;     ...
;   const int nk = K >> 5;
;   Frag F0, F1;
;   GLDS(0, 0);
;   GLDS(1, 1);
;   GLDS(2, 2);
;   GLDS(3, 3);
;   WAIT_VM(12);
;   RAW_BARRIER();
.LBB0_41:
	s_lshl_b32 s6, s94, 8
	s_ashr_i32 s7, s6, 31
	s_lshl_b64 s[6:7], s[6:7], 11
	s_add_u32 s10, s16, s6
	v_mov_b32_e32 v8, v196
	s_addc_u32 s11, s17, s7
	s_ashr_i32 s57, s56, 31
	s_lshl_b64 s[8:9], s[56:57], 19
	s_waitcnt vmcnt(0)
	v_ashrrev_i32_e32 v7, 6, v8
	v_bfe_u32 v0, v8, 2, 4
	v_lshrrev_b32_e32 v10, 4, v8
	v_lshl_or_b32 v0, v7, 5, v0
	s_add_u32 s12, s30, s8
	v_xor_b32_e32 v4, v10, v8
	v_ashrrev_i32_e32 v1, 31, v0
	s_addc_u32 s13, s88, s9
	v_bfe_u32 v9, v8, 5, 1
	v_lshlrev_b64 v[0:1], 11, v[0:1]
	v_lshlrev_b32_e32 v4, 4, v4
	v_lshlrev_b32_e32 v189, 11, v7
	v_lshrrev_b32_e32 v7, 2, v8
	v_lshl_add_u64 v[2:3], s[12:13], 0, v[0:1]
	v_and_b32_e32 v128, 48, v4
	v_lshl_add_u64 v[4:5], s[10:11], 0, v[0:1]
	v_bitop3_b32 v7, v9, v7, 3 bitop3:0x78
	v_and_b32_e32 v6, 31, v8
	v_lshl_add_u64 v[2:3], v[2:3], 0, v[128:129]
	v_lshl_add_u64 v[4:5], v[4:5], 0, v[128:129]
	v_lshlrev_b32_e32 v128, 4, v7
	v_lshrrev_b32_e32 v7, 1, v8
	v_and_or_b32 v6, v7, s65, v6
	v_readfirstlane_b32 s10, v189
	v_or_b32_e32 v9, 0x400, v189
	v_lshlrev_b32_e32 v186, 6, v6
	v_lshlrev_b32_e32 v6, 6, v8
	s_mov_b32 m0, s10
	s_mov_b64 s[12:13], 0x8000
	v_readfirstlane_b32 s10, v9
	v_and_b32_e32 v188, 0x37c0, v6
	global_load_lds_dwordx4 v[2:3], off
	v_lshl_add_u64 v[6:7], v[2:3], 0, s[12:13]
	s_mov_b32 m0, s10
	v_add_u32_e32 v9, 0x4400, v189
	global_load_lds_dwordx4 v[6:7], off
	v_add_u32_e32 v6, 0x4000, v189
	v_xor_b32_e32 v187, 32, v128
	v_readfirstlane_b32 s10, v6
	s_mov_b32 m0, s10
	v_readfirstlane_b32 s10, v9
	v_add_u32_e32 v9, 0x8000, v189
	global_load_lds_dwordx4 v[4:5], off
	v_lshl_add_u64 v[6:7], v[4:5], 0, s[12:13]
	s_mov_b32 m0, s10
	v_readfirstlane_b32 s10, v9
	v_add_u32_e32 v9, 0x8400, v189
	global_load_lds_dwordx4 v[6:7], off
	v_lshl_add_u64 v[6:7], v[2:3], 0, 64
	s_mov_b32 m0, s10
	v_readfirstlane_b32 s10, v9
	v_add_u32_e32 v9, 0xc000, v189
	global_load_lds_dwordx4 v[6:7], off
	v_lshl_add_u64 v[6:7], v[2:3], 0, s[66:67]
	s_mov_b32 m0, s10
	v_readfirstlane_b32 s10, v9
	v_add_u32_e32 v9, 0xc400, v189
	global_load_lds_dwordx4 v[6:7], off
	v_lshl_add_u64 v[6:7], v[4:5], 0, 64
	s_mov_b32 m0, s10
	v_readfirstlane_b32 s10, v9
	v_add_u32_e32 v9, 0x10000, v189
	global_load_lds_dwordx4 v[6:7], off
	v_lshl_add_u64 v[6:7], v[4:5], 0, s[66:67]
	s_mov_b32 m0, s10
	v_readfirstlane_b32 s10, v9
	v_add_u32_e32 v9, 0x10400, v189
	global_load_lds_dwordx4 v[6:7], off
	v_lshl_add_u64 v[6:7], v[2:3], 0, s[68:69]
	s_mov_b32 m0, s10
	v_readfirstlane_b32 s10, v9
	v_add_u32_e32 v9, 0x14000, v189
	global_load_lds_dwordx4 v[6:7], off
	v_lshl_add_u64 v[6:7], v[2:3], 0, s[70:71]
	s_mov_b32 m0, s10
	v_readfirstlane_b32 s10, v9
	v_add_u32_e32 v9, 0x14400, v189
	global_load_lds_dwordx4 v[6:7], off
	v_lshl_add_u64 v[6:7], v[4:5], 0, s[68:69]
	s_mov_b32 m0, s10
	v_readfirstlane_b32 s10, v9
	v_add_u32_e32 v9, 0x18000, v189
	global_load_lds_dwordx4 v[6:7], off
	v_lshl_add_u64 v[6:7], v[4:5], 0, s[70:71]
	s_mov_b32 m0, s10
	v_readfirstlane_b32 s10, v9
	global_load_lds_dwordx4 v[6:7], off
	v_lshl_add_u64 v[6:7], v[2:3], 0, s[72:73]
	s_mov_b32 m0, s10
	v_lshl_add_u64 v[2:3], v[2:3], 0, s[74:75]
	global_load_lds_dwordx4 v[6:7], off
	v_add_u32_e32 v6, 0x18400, v189
	s_nop 0
	v_readfirstlane_b32 s10, v6
	v_add_u32_e32 v6, 0x1c000, v189
	s_mov_b32 m0, s10
	v_readfirstlane_b32 s10, v6
	global_load_lds_dwordx4 v[2:3], off
	v_lshl_add_u64 v[2:3], v[4:5], 0, s[72:73]
	s_mov_b32 m0, s10
	s_nop 0
	global_load_lds_dwordx4 v[2:3], off
	v_lshl_add_u64 v[2:3], v[4:5], 0, s[74:75]
	v_add_u32_e32 v4, 0x1c400, v189
	s_nop 0
	v_readfirstlane_b32 s10, v4
	s_mov_b32 m0, s10
	v_bitop3_b32 v4, v10, 3, v8 bitop3:0x48
	global_load_lds_dwordx4 v[2:3], off
	v_mov_b32_e32 v5, 0
	v_mov_b32_e32 v6, 0
	v_mov_b32_e32 v7, 0
	v_mov_b32_e32 v8, 0
	v_mov_b32_e32 v9, 0
	v_mov_b32_e32 v10, 0
	v_mov_b32_e32 v11, 0
	v_mov_b32_e32 v12, 0
	v_mov_b32_e32 v13, 0
	v_mov_b32_e32 v14, 0
	v_mov_b32_e32 v15, 0
	v_mov_b32_e32 v16, 0
	v_mov_b32_e32 v17, 0
	v_mov_b32_e32 v18, 0
	v_mov_b32_e32 v19, 0
	v_mov_b32_e32 v20, 0
	v_mov_b32_e32 v21, 0
	v_mov_b32_e32 v22, 0
	v_mov_b32_e32 v23, 0
	v_mov_b32_e32 v24, 0
	v_mov_b32_e32 v25, 0
	v_mov_b32_e32 v26, 0
	v_mov_b32_e32 v27, 0
	v_mov_b32_e32 v28, 0
	v_mov_b32_e32 v29, 0
	v_mov_b32_e32 v30, 0
	v_mov_b32_e32 v31, 0
	v_mov_b32_e32 v32, 0
	v_mov_b32_e32 v33, 0
	v_mov_b32_e32 v34, 0
	v_mov_b32_e32 v35, 0
	v_mov_b32_e32 v36, 0
	v_mov_b32_e32 v37, 0
	v_mov_b32_e32 v38, 0
	v_mov_b32_e32 v39, 0
	v_mov_b32_e32 v40, 0
	v_mov_b32_e32 v41, 0
	v_mov_b32_e32 v42, 0
	v_mov_b32_e32 v43, 0
	v_mov_b32_e32 v44, 0
	v_mov_b32_e32 v45, 0
	v_mov_b32_e32 v46, 0
	v_mov_b32_e32 v47, 0
	v_mov_b32_e32 v48, 0
	v_mov_b32_e32 v49, 0
	v_mov_b32_e32 v50, 0
	v_mov_b32_e32 v51, 0
	v_mov_b32_e32 v52, 0
	v_mov_b32_e32 v53, 0
	v_mov_b32_e32 v54, 0
	v_mov_b32_e32 v55, 0
	v_mov_b32_e32 v56, 0
	v_mov_b32_e32 v57, 0
	v_mov_b32_e32 v58, 0
	v_mov_b32_e32 v59, 0
	v_mov_b32_e32 v60, 0
	v_mov_b32_e32 v61, 0
	v_mov_b32_e32 v62, 0
	v_mov_b32_e32 v63, 0
	v_mov_b32_e32 v64, 0
	v_mov_b32_e32 v65, 0
	v_mov_b32_e32 v66, 0
	v_mov_b32_e32 v67, 0
	v_mov_b32_e32 v68, 0
	v_mov_b32_e32 v69, 0
	v_mov_b32_e32 v70, 0
	v_mov_b32_e32 v71, 0
	v_mov_b32_e32 v72, 0
	v_mov_b32_e32 v73, 0
	v_mov_b32_e32 v74, 0
	v_mov_b32_e32 v75, 0
	v_mov_b32_e32 v76, 0
	v_mov_b32_e32 v77, 0
	v_mov_b32_e32 v78, 0
	v_mov_b32_e32 v79, 0
	v_mov_b32_e32 v80, 0
	v_mov_b32_e32 v81, 0
	v_mov_b32_e32 v82, 0
	v_mov_b32_e32 v83, 0
	v_mov_b32_e32 v84, 0
	v_mov_b32_e32 v85, 0
	v_mov_b32_e32 v86, 0
	v_mov_b32_e32 v87, 0
	v_mov_b32_e32 v88, 0
	v_mov_b32_e32 v89, 0
	v_mov_b32_e32 v90, 0
	v_mov_b32_e32 v91, 0
	v_mov_b32_e32 v92, 0
	v_mov_b32_e32 v93, 0
	v_mov_b32_e32 v94, 0
	v_mov_b32_e32 v95, 0
	v_mov_b32_e32 v96, 0
	v_mov_b32_e32 v97, 0
	v_mov_b32_e32 v98, 0
	v_mov_b32_e32 v99, 0
	v_mov_b32_e32 v100, 0
	v_mov_b32_e32 v101, 0
	v_mov_b32_e32 v102, 0
	v_mov_b32_e32 v103, 0
	v_mov_b32_e32 v104, 0
	v_mov_b32_e32 v105, 0
	v_mov_b32_e32 v106, 0
	v_mov_b32_e32 v107, 0
	v_mov_b32_e32 v108, 0
	v_mov_b32_e32 v109, 0
	v_mov_b32_e32 v110, 0
	v_mov_b32_e32 v111, 0
	v_mov_b32_e32 v112, 0
	v_mov_b32_e32 v113, 0
	v_mov_b32_e32 v114, 0
	v_mov_b32_e32 v115, 0
	v_mov_b32_e32 v116, 0
	v_mov_b32_e32 v117, 0
	v_mov_b32_e32 v118, 0
	v_mov_b32_e32 v119, 0
	v_mov_b32_e32 v120, 0
	v_mov_b32_e32 v121, 0
	v_mov_b32_e32 v122, 0
	v_mov_b32_e32 v123, 0
	v_mov_b32_e32 v124, 0
	v_mov_b32_e32 v125, 0
	v_mov_b32_e32 v126, 0
	v_mov_b32_e32 v127, 0
	s_waitcnt vmcnt(12)
	v_or_b32_e32 v2, v186, v128
	s_waitcnt lgkmcnt(0)
	s_barrier
; #define RAW_BARRIER() do { asm volatile("s_waitcnt lgkmcnt(0)" ::: "memory"); __builtin_amdgcn_s_barrier(); } while (0)
; #define WAIT_VM(n) asm volatile("s_waitcnt vmcnt(" #n ")" ::: "memory")
; template <bool AF32>
; DI void gemm_main(const void* Ap, int lda, const short* Bp, int K, char* smem, f32x16 (&acc)[4][2]) {
;     ...
;   const int lch = (lane & 3) ^ ((lane >> 4) & 3);
;   const short* ga = (const short*)Ap + (size_t)(w * 32 + (lane >> 2)) * lda + lch * 8;
;   const short* gb = Bp + (size_t)(w * 32 + (lane >> 2)) * K + lch * 8;
;   const size_t a16 = (size_t)16 * lda, b16 = (size_t)16 * K;
;   char* lbase = smem + w * 2048;
;     ...
;   const int x = (r >> 2) & 3;
;   const int off0 = ((h ^ x) << 4);
;   const int aoff = (wm * 128 + r) * 64, boff = GBOFF + (wn * 64 + r) * 64;
;   struct Frag { bf16x8 a[4], b0, b1; };
;     ...
;   const int nk = K >> 5;
;   Frag F0, F1;
;   GLDS(0, 0);
;   GLDS(1, 1);
;   GLDS(2, 2);
;   GLDS(3, 3);
;   WAIT_VM(12);
;   RAW_BARRIER();
;   LOADF(F0, 0, 0);
	ds_read_b128 v[130:133], v2 offset:6144
	ds_read_b128 v[142:145], v2 offset:4096
	ds_read_b128 v[146:149], v2 offset:2048
	ds_read_b128 v[150:153], v2
	v_or_b32_e32 v2, v188, v128
	ds_read_b128 v[134:137], v2 offset:18432
	ds_read_b128 v[138:141], v2 offset:16384
	v_lshl_add_u64 v[2:3], s[8:9], 0, v[0:1]
	v_lshlrev_b32_e32 v4, 4, v4
	v_lshl_add_u64 v[0:1], s[6:7], 0, v[0:1]
	v_or_b32_e32 v0, v0, v4
	v_or_b32_e32 v2, v2, v4
	v_lshl_add_u64 v[180:181], s[16:17], 0, v[0:1]
	v_mov_b32_e32 v0, 0
	v_lshl_add_u64 v[178:179], s[16:17], 0, v[2:3]
	s_mov_b64 s[6:7], 0
	s_mov_b32 s8, 0
	v_mov_b32_e32 v1, v0
	v_mov_b32_e32 v2, v0
	v_mov_b32_e32 v3, v0
	v_mov_b32_e32 v4, v0

; DI int my_tid() { int t = threadIdx.x; asm volatile("" : "+v"(t)); return t; }
; #define RAW_BARRIER() do { asm volatile("s_waitcnt lgkmcnt(0)" ::: "memory"); __builtin_amdgcn_s_barrier(); } while (0)
; #define WAIT_VM(n) asm volatile("s_waitcnt vmcnt(" #n ")" ::: "memory")
; template <bool AF32>
; DI void gemm_main(const void* Ap, int lda, const short* Bp, int K, char* smem, f32x16 (&acc)[4][2]) {
;   const int tid = my_tid(), lane = tid & 63, w = tid >> 6, r = lane & 31, h = lane >> 5;
;   const int wm = w >> 2, wn = w & 3;
; #pragma unroll
;   for (int a = 0; a < 4; a++)
; #pragma unroll
;     for (int b = 0; b < 2; b++)
; #pragma unroll
;       for (int i = 0; i < 16; i++) acc[a][b][i] = 0.f;
;   const int lch = (lane & 3) ^ ((lane >> 4) & 3);
;   const short* ga = (const short*)Ap + (size_t)(w * 32 + (lane >> 2)) * lda + lch * 8;
;   const short* gb = Bp + (size_t)(w * 32 + (lane >> 2)) * K + lch * 8;
;   const size_t a16 = (size_t)16 * lda, b16 = (size_t)16 * K;
;   char* lbase = smem + w * 2048;
;     ...
;   const int x = (r >> 2) & 3;
;   const int off0 = ((h ^ x) << 4);
;   const int aoff = (wm * 128 + r) * 64, boff = GBOFF + (wn * 64 + r) * 64;
;   struct Frag { bf16x8 a[4], b0, b1; };
;     ...
;   const int nk = K >> 5;
;   Frag F0, F1;
;   GLDS(0, 0);
;   GLDS(1, 1);
;   GLDS(2, 2);
;   GLDS(3, 3);
;   WAIT_VM(12);
;   RAW_BARRIER();
.LBB0_449:
	s_lshl_b32 s7, s6, 1
	s_and_b32 s8, s7, 0x1f8
	s_or_b32 s9, s8, s52
	s_lshl_b32 s7, s9, 19
	s_add_u32 s12, s37, s7
	s_addc_u32 s13, s94, 0
	s_lshl_b32 s7, s6, 8
	s_and_b32 s10, s7, 0x300
	v_mov_b32_e32 v8, v196
	s_lshl_b32 s11, s10, 11
	s_or_b32 s7, s11, s97
	s_waitcnt vmcnt(0)
	v_ashrrev_i32_e32 v7, 6, v8
	v_bfe_u32 v0, v8, 2, 4
	v_lshrrev_b32_e32 v10, 4, v8
	v_lshl_or_b32 v0, v7, 5, v0
	s_add_u32 s28, s95, s7
	v_xor_b32_e32 v4, v10, v8
	v_ashrrev_i32_e32 v1, 31, v0
	s_addc_u32 s29, s96, 0
	v_bfe_u32 v9, v8, 5, 1
	v_lshlrev_b64 v[0:1], 11, v[0:1]
	v_lshlrev_b32_e32 v4, 4, v4
	v_lshlrev_b32_e32 v189, 11, v7
	v_lshrrev_b32_e32 v7, 2, v8
	v_lshl_add_u64 v[2:3], s[12:13], 0, v[0:1]
	v_and_b32_e32 v128, 48, v4
	v_lshl_add_u64 v[4:5], s[28:29], 0, v[0:1]
	v_bitop3_b32 v7, v9, v7, 3 bitop3:0x78
	v_and_b32_e32 v6, 31, v8
	v_lshl_add_u64 v[2:3], v[2:3], 0, v[128:129]
	v_lshl_add_u64 v[4:5], v[4:5], 0, v[128:129]
	v_lshlrev_b32_e32 v128, 4, v7
	v_lshrrev_b32_e32 v7, 1, v8
	v_and_or_b32 v6, v7, s65, v6
	v_readfirstlane_b32 s7, v189
	v_or_b32_e32 v9, 0x400, v189
	v_lshlrev_b32_e32 v186, 6, v6
	v_lshlrev_b32_e32 v6, 6, v8
	s_mov_b32 m0, s7
	s_mov_b64 s[0:1], 0x8000
	v_readfirstlane_b32 s7, v9
	v_and_b32_e32 v188, 0x37c0, v6
	global_load_lds_dwordx4 v[2:3], off
	v_lshl_add_u64 v[6:7], v[2:3], 0, s[0:1]
	s_mov_b32 m0, s7
	v_add_u32_e32 v9, 0x4400, v189
	global_load_lds_dwordx4 v[6:7], off
	v_add_u32_e32 v6, 0x4000, v189
	s_lshl_b32 s6, s6, 20
	v_readfirstlane_b32 s7, v6
	s_mov_b32 m0, s7
	v_readfirstlane_b32 s7, v9
	v_add_u32_e32 v9, 0x8000, v189
	global_load_lds_dwordx4 v[4:5], off
	v_lshl_add_u64 v[6:7], v[4:5], 0, s[0:1]
	s_mov_b32 m0, s7
	v_readfirstlane_b32 s7, v9
	v_add_u32_e32 v9, 0x8400, v189
	global_load_lds_dwordx4 v[6:7], off
	v_lshl_add_u64 v[6:7], v[2:3], 0, 64
	s_mov_b32 m0, s7
	v_readfirstlane_b32 s7, v9
	v_add_u32_e32 v9, 0xc000, v189
	global_load_lds_dwordx4 v[6:7], off
	v_lshl_add_u64 v[6:7], v[2:3], 0, s[66:67]
	s_mov_b32 m0, s7
	v_readfirstlane_b32 s7, v9
	v_add_u32_e32 v9, 0xc400, v189
	global_load_lds_dwordx4 v[6:7], off
	v_lshl_add_u64 v[6:7], v[4:5], 0, 64
	s_mov_b32 m0, s7
	v_readfirstlane_b32 s7, v9
	v_add_u32_e32 v9, 0x10000, v189
	global_load_lds_dwordx4 v[6:7], off
	v_lshl_add_u64 v[6:7], v[4:5], 0, s[66:67]
	s_mov_b32 m0, s7
	v_readfirstlane_b32 s7, v9
	v_add_u32_e32 v9, 0x10400, v189
	global_load_lds_dwordx4 v[6:7], off
	v_lshl_add_u64 v[6:7], v[2:3], 0, s[68:69]
	s_mov_b32 m0, s7
	v_readfirstlane_b32 s7, v9
	v_add_u32_e32 v9, 0x14000, v189
	global_load_lds_dwordx4 v[6:7], off
	v_lshl_add_u64 v[6:7], v[2:3], 0, s[70:71]
	s_mov_b32 m0, s7
	v_readfirstlane_b32 s7, v9
	v_add_u32_e32 v9, 0x14400, v189
	global_load_lds_dwordx4 v[6:7], off
	v_lshl_add_u64 v[6:7], v[4:5], 0, s[68:69]
	s_mov_b32 m0, s7
	v_readfirstlane_b32 s7, v9
	v_add_u32_e32 v9, 0x18000, v189
	global_load_lds_dwordx4 v[6:7], off
	v_lshl_add_u64 v[6:7], v[4:5], 0, s[70:71]
	s_mov_b32 m0, s7
	v_readfirstlane_b32 s7, v9
	global_load_lds_dwordx4 v[6:7], off
	v_lshl_add_u64 v[6:7], v[2:3], 0, s[72:73]
	s_mov_b32 m0, s7
	v_lshl_add_u64 v[2:3], v[2:3], 0, s[74:75]
	global_load_lds_dwordx4 v[6:7], off
	v_add_u32_e32 v6, 0x18400, v189
	s_and_b32 s6, s6, 0xfc00000
	v_readfirstlane_b32 s7, v6
	v_add_u32_e32 v6, 0x1c000, v189
	s_mov_b32 m0, s7
	v_readfirstlane_b32 s7, v6
	global_load_lds_dwordx4 v[2:3], off
	v_lshl_add_u64 v[2:3], v[4:5], 0, s[72:73]
	s_mov_b32 m0, s7
	s_or_b32 s6, s64, s6
	global_load_lds_dwordx4 v[2:3], off
	v_lshl_add_u64 v[2:3], v[4:5], 0, s[74:75]
	v_add_u32_e32 v4, 0x1c400, v189
	s_add_u32 s6, s14, s6
	v_readfirstlane_b32 s7, v4
	s_mov_b32 m0, s7
	s_addc_u32 s7, s15, 0
	global_load_lds_dwordx4 v[2:3], off
	v_mov_b32_e32 v5, 0
	v_mov_b32_e32 v6, 0
	v_mov_b32_e32 v7, 0
	v_mov_b32_e32 v9, 0
	v_mov_b32_e32 v11, 0
	v_mov_b32_e32 v12, 0
	v_mov_b32_e32 v13, 0
	v_mov_b32_e32 v14, 0
	v_mov_b32_e32 v15, 0
	v_mov_b32_e32 v16, 0
	v_mov_b32_e32 v17, 0
	v_mov_b32_e32 v18, 0
	v_mov_b32_e32 v19, 0
	v_mov_b32_e32 v20, 0
	v_mov_b32_e32 v21, 0
	v_mov_b32_e32 v22, 0
	v_mov_b32_e32 v23, 0
	v_mov_b32_e32 v24, 0
	v_mov_b32_e32 v25, 0
	v_mov_b32_e32 v26, 0
	v_mov_b32_e32 v27, 0
	v_mov_b32_e32 v28, 0
	v_mov_b32_e32 v29, 0
	v_mov_b32_e32 v30, 0
	v_mov_b32_e32 v31, 0
	v_mov_b32_e32 v32, 0
	v_mov_b32_e32 v33, 0
	v_mov_b32_e32 v34, 0
	v_mov_b32_e32 v35, 0
	v_mov_b32_e32 v36, 0
	v_mov_b32_e32 v37, 0
	v_mov_b32_e32 v38, 0
	v_mov_b32_e32 v39, 0
	v_mov_b32_e32 v40, 0
	v_mov_b32_e32 v41, 0
	v_mov_b32_e32 v42, 0
	v_mov_b32_e32 v43, 0
	v_mov_b32_e32 v44, 0
	v_mov_b32_e32 v45, 0
	v_mov_b32_e32 v46, 0
	v_mov_b32_e32 v47, 0
	v_mov_b32_e32 v48, 0
	v_mov_b32_e32 v49, 0
	v_mov_b32_e32 v50, 0
	v_mov_b32_e32 v51, 0
	v_mov_b32_e32 v52, 0
	v_mov_b32_e32 v53, 0
	v_mov_b32_e32 v54, 0
	v_mov_b32_e32 v55, 0
	v_mov_b32_e32 v56, 0
	v_mov_b32_e32 v57, 0
	v_mov_b32_e32 v58, 0
	v_mov_b32_e32 v59, 0
	v_mov_b32_e32 v60, 0
	v_mov_b32_e32 v61, 0
	v_mov_b32_e32 v62, 0
	v_mov_b32_e32 v63, 0
	v_mov_b32_e32 v64, 0
	v_mov_b32_e32 v65, 0
	v_mov_b32_e32 v66, 0
	v_mov_b32_e32 v67, 0
	v_mov_b32_e32 v68, 0
	v_mov_b32_e32 v69, 0
	v_mov_b32_e32 v70, 0
	v_mov_b32_e32 v71, 0
	v_mov_b32_e32 v72, 0
	v_mov_b32_e32 v73, 0
	v_mov_b32_e32 v74, 0
	v_mov_b32_e32 v75, 0
	v_mov_b32_e32 v76, 0
	v_mov_b32_e32 v77, 0
	v_mov_b32_e32 v78, 0
	v_mov_b32_e32 v79, 0
	v_mov_b32_e32 v80, 0
	v_mov_b32_e32 v81, 0
	v_mov_b32_e32 v82, 0
	v_mov_b32_e32 v83, 0
	v_mov_b32_e32 v84, 0
	v_mov_b32_e32 v85, 0
	v_mov_b32_e32 v86, 0
	v_mov_b32_e32 v87, 0
	v_mov_b32_e32 v88, 0
	v_mov_b32_e32 v89, 0
	v_mov_b32_e32 v90, 0
	v_mov_b32_e32 v91, 0
	v_mov_b32_e32 v92, 0
	v_mov_b32_e32 v93, 0
	v_mov_b32_e32 v94, 0
	v_mov_b32_e32 v95, 0
	v_mov_b32_e32 v96, 0
	v_mov_b32_e32 v97, 0
	v_mov_b32_e32 v98, 0
	v_mov_b32_e32 v99, 0
	v_mov_b32_e32 v100, 0
	v_mov_b32_e32 v101, 0
	v_mov_b32_e32 v102, 0
	v_mov_b32_e32 v103, 0
	v_mov_b32_e32 v104, 0
	v_mov_b32_e32 v105, 0
	v_mov_b32_e32 v106, 0
	v_mov_b32_e32 v107, 0
	v_mov_b32_e32 v108, 0
	v_mov_b32_e32 v109, 0
	v_mov_b32_e32 v110, 0
	v_mov_b32_e32 v111, 0
	v_mov_b32_e32 v112, 0
	v_mov_b32_e32 v113, 0
	v_mov_b32_e32 v114, 0
	v_mov_b32_e32 v115, 0
	v_mov_b32_e32 v116, 0
	v_mov_b32_e32 v117, 0
	v_mov_b32_e32 v118, 0
	v_mov_b32_e32 v119, 0
	v_mov_b32_e32 v120, 0
	v_mov_b32_e32 v121, 0
	v_mov_b32_e32 v122, 0
	v_mov_b32_e32 v123, 0
	v_mov_b32_e32 v124, 0
	v_mov_b32_e32 v125, 0
	v_mov_b32_e32 v126, 0
	v_mov_b32_e32 v127, 0
	s_waitcnt vmcnt(12)
	v_or_b32_e32 v2, v186, v128
	s_waitcnt lgkmcnt(0)
	s_barrier
; #define RAW_BARRIER() do { asm volatile("s_waitcnt lgkmcnt(0)" ::: "memory"); __builtin_amdgcn_s_barrier(); } while (0)
; #define WAIT_VM(n) asm volatile("s_waitcnt vmcnt(" #n ")" ::: "memory")
; template <bool AF32>
; DI void gemm_main(const void* Ap, int lda, const short* Bp, int K, char* smem, f32x16 (&acc)[4][2]) {
;     ...
;   const int lch = (lane & 3) ^ ((lane >> 4) & 3);
;   const short* ga = (const short*)Ap + (size_t)(w * 32 + (lane >> 2)) * lda + lch * 8;
;   const short* gb = Bp + (size_t)(w * 32 + (lane >> 2)) * K + lch * 8;
;   const size_t a16 = (size_t)16 * lda, b16 = (size_t)16 * K;
;   char* lbase = smem + w * 2048;
;     ...
;   const int x = (r >> 2) & 3;
;   const int off0 = ((h ^ x) << 4);
;   const int aoff = (wm * 128 + r) * 64, boff = GBOFF + (wn * 64 + r) * 64;
;   struct Frag { bf16x8 a[4], b0, b1; };
;     ...
;   const int nk = K >> 5;
;   Frag F0, F1;
;   GLDS(0, 0);
;   GLDS(1, 1);
;   GLDS(2, 2);
;   GLDS(3, 3);
;   WAIT_VM(12);
;   RAW_BARRIER();
;   LOADF(F0, 0, 0);
	ds_read_b128 v[130:133], v2 offset:6144
	ds_read_b128 v[142:145], v2 offset:4096
	ds_read_b128 v[146:149], v2 offset:2048
	ds_read_b128 v[150:153], v2
	v_or_b32_e32 v2, v188, v128
	ds_read_b128 v[134:137], v2 offset:18432
	ds_read_b128 v[138:141], v2 offset:16384
	v_bitop3_b32 v2, v10, 3, v8 bitop3:0x48
	v_lshl_or_b32 v0, v2, 4, v0
	v_lshl_add_u64 v[178:179], s[6:7], 0, v[0:1]
	s_add_i32 s6, s97, s11
	s_add_u32 s6, s14, s6
	s_addc_u32 s7, s15, 0
	v_lshl_add_u64 v[180:181], s[6:7], 0, v[0:1]
	v_mov_b32_e32 v0, 0
	v_xor_b32_e32 v187, 32, v128
	s_mov_b64 s[6:7], 0
	s_mov_b32 s11, 0
	v_mov_b32_e32 v1, v0
	v_mov_b32_e32 v2, v0
	v_mov_b32_e32 v3, v0
	v_mov_b32_e32 v4, v0
	v_mov_b32_e32 v8, v0
	v_mov_b32_e32 v10, v0

; DI int my_tid() { int t = threadIdx.x; asm volatile("" : "+v"(t)); return t; }
; #define RAW_BARRIER() do { asm volatile("s_waitcnt lgkmcnt(0)" ::: "memory"); __builtin_amdgcn_s_barrier(); } while (0)
; #define WAIT_VM(n) asm volatile("s_waitcnt vmcnt(" #n ")" ::: "memory")
; template <bool AF32>
; DI void gemm_main(const void* Ap, int lda, const short* Bp, int K, char* smem, f32x16 (&acc)[4][2]) {
;   const int tid = my_tid(), lane = tid & 63, w = tid >> 6, r = lane & 31, h = lane >> 5;
;   const int wm = w >> 2, wn = w & 3;
; #pragma unroll
;   for (int a = 0; a < 4; a++)
; #pragma unroll
;     for (int b = 0; b < 2; b++)
; #pragma unroll
;       for (int i = 0; i < 16; i++) acc[a][b][i] = 0.f;
;   const int lch = (lane & 3) ^ ((lane >> 4) & 3);
;   const short* ga = (const short*)Ap + (size_t)(w * 32 + (lane >> 2)) * lda + lch * 8;
;   const short* gb = Bp + (size_t)(w * 32 + (lane >> 2)) * K + lch * 8;
;   const size_t a16 = (size_t)16 * lda, b16 = (size_t)16 * K;
;   char* lbase = smem + w * 2048;
;     ...
;   const int x = (r >> 2) & 3;
;   const int off0 = ((h ^ x) << 4);
;   const int aoff = (wm * 128 + r) * 64, boff = GBOFF + (wn * 64 + r) * 64;
;   struct Frag { bf16x8 a[4], b0, b1; };
;     ...
;   const int nk = K >> 5;
;   Frag F0, F1;
;   GLDS(0, 0);
;   GLDS(1, 1);
;   GLDS(2, 2);
;   GLDS(3, 3);
;   WAIT_VM(12);
;   RAW_BARRIER();
.LBB0_664:
	s_lshl_b32 s6, s90, 8
	s_ashr_i32 s7, s6, 31
	s_mul_i32 s8, s17, 0xb00
	s_add_u32 s8, s6, s8
	s_addc_u32 s9, s7, 0
	s_lshl_b64 s[8:9], s[8:9], 11
	s_add_u32 s10, s86, s8
	v_mov_b32_e32 v8, v196
	s_addc_u32 s11, s87, s9
	s_ashr_i32 s39, s38, 31
	s_lshl_b64 s[8:9], s[38:39], 19
	s_waitcnt vmcnt(0)
	v_ashrrev_i32_e32 v7, 6, v8
	v_bfe_u32 v0, v8, 2, 4
	v_lshrrev_b32_e32 v10, 4, v8
	v_lshl_or_b32 v0, v7, 5, v0
	s_add_u32 s12, s18, s8
	v_xor_b32_e32 v4, v10, v8
	v_ashrrev_i32_e32 v1, 31, v0
	s_addc_u32 s13, s19, s9
	v_bfe_u32 v9, v8, 5, 1
	v_lshlrev_b64 v[0:1], 11, v[0:1]
	v_lshlrev_b32_e32 v4, 4, v4
	v_lshlrev_b32_e32 v189, 11, v7
	v_lshrrev_b32_e32 v7, 2, v8
	v_lshl_add_u64 v[2:3], s[12:13], 0, v[0:1]
	v_and_b32_e32 v128, 48, v4
	v_lshl_add_u64 v[4:5], s[10:11], 0, v[0:1]
	v_bitop3_b32 v7, v9, v7, 3 bitop3:0x78
	v_and_b32_e32 v6, 31, v8
	v_lshl_add_u64 v[2:3], v[2:3], 0, v[128:129]
	v_lshl_add_u64 v[4:5], v[4:5], 0, v[128:129]
	v_lshlrev_b32_e32 v128, 4, v7
	v_lshrrev_b32_e32 v7, 1, v8
	v_and_or_b32 v6, v7, s65, v6
	v_readfirstlane_b32 s10, v189
	v_or_b32_e32 v9, 0x400, v189
	v_lshlrev_b32_e32 v186, 6, v6
	v_lshlrev_b32_e32 v6, 6, v8
	s_mov_b32 m0, s10
	s_mov_b64 s[12:13], 0x8000
	v_readfirstlane_b32 s10, v9
	v_and_b32_e32 v188, 0x37c0, v6
	global_load_lds_dwordx4 v[2:3], off
	v_lshl_add_u64 v[6:7], v[2:3], 0, s[12:13]
	s_mov_b32 m0, s10
	v_add_u32_e32 v9, 0x4400, v189
	global_load_lds_dwordx4 v[6:7], off
	v_add_u32_e32 v6, 0x4000, v189
	s_lshl_b64 s[6:7], s[6:7], 11
	v_readfirstlane_b32 s10, v6
	s_mov_b32 m0, s10
	v_readfirstlane_b32 s10, v9
	v_add_u32_e32 v9, 0x8000, v189
	global_load_lds_dwordx4 v[4:5], off
	v_lshl_add_u64 v[6:7], v[4:5], 0, s[12:13]
	s_mov_b32 m0, s10
	v_readfirstlane_b32 s10, v9
	v_add_u32_e32 v9, 0x8400, v189
	global_load_lds_dwordx4 v[6:7], off
	v_lshl_add_u64 v[6:7], v[2:3], 0, 64
	s_mov_b32 m0, s10
	v_readfirstlane_b32 s10, v9
	v_add_u32_e32 v9, 0xc000, v189
	global_load_lds_dwordx4 v[6:7], off
	v_lshl_add_u64 v[6:7], v[2:3], 0, s[66:67]
	s_mov_b32 m0, s10
	v_readfirstlane_b32 s10, v9
	v_add_u32_e32 v9, 0xc400, v189
	global_load_lds_dwordx4 v[6:7], off
	v_lshl_add_u64 v[6:7], v[4:5], 0, 64
	s_mov_b32 m0, s10
	v_readfirstlane_b32 s10, v9
	v_add_u32_e32 v9, 0x10000, v189
	global_load_lds_dwordx4 v[6:7], off
	v_lshl_add_u64 v[6:7], v[4:5], 0, s[66:67]
	s_mov_b32 m0, s10
	v_readfirstlane_b32 s10, v9
	v_add_u32_e32 v9, 0x10400, v189
	global_load_lds_dwordx4 v[6:7], off
	v_lshl_add_u64 v[6:7], v[2:3], 0, s[68:69]
	s_mov_b32 m0, s10
	v_readfirstlane_b32 s10, v9
	v_add_u32_e32 v9, 0x14000, v189
	global_load_lds_dwordx4 v[6:7], off
	v_lshl_add_u64 v[6:7], v[2:3], 0, s[70:71]
	s_mov_b32 m0, s10
	v_readfirstlane_b32 s10, v9
	v_add_u32_e32 v9, 0x14400, v189
	global_load_lds_dwordx4 v[6:7], off
	v_lshl_add_u64 v[6:7], v[4:5], 0, s[68:69]
	s_mov_b32 m0, s10
	v_readfirstlane_b32 s10, v9
	v_add_u32_e32 v9, 0x18000, v189
	global_load_lds_dwordx4 v[6:7], off
	v_lshl_add_u64 v[6:7], v[4:5], 0, s[70:71]
	s_mov_b32 m0, s10
	v_readfirstlane_b32 s10, v9
	global_load_lds_dwordx4 v[6:7], off
	v_lshl_add_u64 v[6:7], v[2:3], 0, s[72:73]
	s_mov_b32 m0, s10
	v_lshl_add_u64 v[2:3], v[2:3], 0, s[74:75]
	global_load_lds_dwordx4 v[6:7], off
	v_add_u32_e32 v6, 0x18400, v189
	v_xor_b32_e32 v187, 32, v128
	v_readfirstlane_b32 s10, v6
	v_add_u32_e32 v6, 0x1c000, v189
	s_mov_b32 m0, s10
	v_readfirstlane_b32 s10, v6
	global_load_lds_dwordx4 v[2:3], off
	v_lshl_add_u64 v[2:3], v[4:5], 0, s[72:73]
	s_mov_b32 m0, s10
	s_nop 0
	global_load_lds_dwordx4 v[2:3], off
	v_lshl_add_u64 v[2:3], v[4:5], 0, s[74:75]
	v_add_u32_e32 v4, 0x1c400, v189
	s_nop 0
	v_readfirstlane_b32 s10, v4
	s_mov_b32 m0, s10
	v_bitop3_b32 v4, v10, 3, v8 bitop3:0x48
	global_load_lds_dwordx4 v[2:3], off
	v_mov_b32_e32 v5, 0
	v_mov_b32_e32 v6, 0
	v_mov_b32_e32 v7, 0
	v_mov_b32_e32 v8, 0
	v_mov_b32_e32 v9, 0
	v_mov_b32_e32 v10, 0
	v_mov_b32_e32 v11, 0
	v_mov_b32_e32 v12, 0
	v_mov_b32_e32 v13, 0
	v_mov_b32_e32 v14, 0
	v_mov_b32_e32 v15, 0
	v_mov_b32_e32 v16, 0
	v_mov_b32_e32 v17, 0
	v_mov_b32_e32 v18, 0
	v_mov_b32_e32 v19, 0
	v_mov_b32_e32 v20, 0
	v_mov_b32_e32 v21, 0
	v_mov_b32_e32 v22, 0
	v_mov_b32_e32 v23, 0
	v_mov_b32_e32 v24, 0
	v_mov_b32_e32 v25, 0
	v_mov_b32_e32 v26, 0
	v_mov_b32_e32 v27, 0
	v_mov_b32_e32 v28, 0
	v_mov_b32_e32 v29, 0
	v_mov_b32_e32 v30, 0
	v_mov_b32_e32 v31, 0
	v_mov_b32_e32 v32, 0
	v_mov_b32_e32 v33, 0
	v_mov_b32_e32 v34, 0
	v_mov_b32_e32 v35, 0
	v_mov_b32_e32 v36, 0
	v_mov_b32_e32 v37, 0
	v_mov_b32_e32 v38, 0
	v_mov_b32_e32 v39, 0
	v_mov_b32_e32 v40, 0
	v_mov_b32_e32 v41, 0
	v_mov_b32_e32 v42, 0
	v_mov_b32_e32 v43, 0
	v_mov_b32_e32 v44, 0
	v_mov_b32_e32 v45, 0
	v_mov_b32_e32 v46, 0
	v_mov_b32_e32 v47, 0
	v_mov_b32_e32 v48, 0
	v_mov_b32_e32 v49, 0
	v_mov_b32_e32 v50, 0
	v_mov_b32_e32 v51, 0
	v_mov_b32_e32 v52, 0
	v_mov_b32_e32 v53, 0
	v_mov_b32_e32 v54, 0
	v_mov_b32_e32 v55, 0
	v_mov_b32_e32 v56, 0
	v_mov_b32_e32 v57, 0
	v_mov_b32_e32 v58, 0
	v_mov_b32_e32 v59, 0
	v_mov_b32_e32 v60, 0
	v_mov_b32_e32 v61, 0
	v_mov_b32_e32 v62, 0
	v_mov_b32_e32 v63, 0
	v_mov_b32_e32 v64, 0
	v_mov_b32_e32 v65, 0
	v_mov_b32_e32 v66, 0
	v_mov_b32_e32 v67, 0
	v_mov_b32_e32 v68, 0
	v_mov_b32_e32 v69, 0
	v_mov_b32_e32 v70, 0
	v_mov_b32_e32 v71, 0
	v_mov_b32_e32 v72, 0
	v_mov_b32_e32 v73, 0
	v_mov_b32_e32 v74, 0
	v_mov_b32_e32 v75, 0
	v_mov_b32_e32 v76, 0
	v_mov_b32_e32 v77, 0
	v_mov_b32_e32 v78, 0
	v_mov_b32_e32 v79, 0
	v_mov_b32_e32 v80, 0
	v_mov_b32_e32 v81, 0
	v_mov_b32_e32 v82, 0
	v_mov_b32_e32 v83, 0
	v_mov_b32_e32 v84, 0
	v_mov_b32_e32 v85, 0
	v_mov_b32_e32 v86, 0
	v_mov_b32_e32 v87, 0
	v_mov_b32_e32 v88, 0
	v_mov_b32_e32 v89, 0
	v_mov_b32_e32 v90, 0
	v_mov_b32_e32 v91, 0
	v_mov_b32_e32 v92, 0
	v_mov_b32_e32 v93, 0
	v_mov_b32_e32 v94, 0
	v_mov_b32_e32 v95, 0
	v_mov_b32_e32 v96, 0
	v_mov_b32_e32 v97, 0
	v_mov_b32_e32 v98, 0
	v_mov_b32_e32 v99, 0
	v_mov_b32_e32 v100, 0
	v_mov_b32_e32 v101, 0
	v_mov_b32_e32 v102, 0
	v_mov_b32_e32 v103, 0
	v_mov_b32_e32 v104, 0
	v_mov_b32_e32 v105, 0
	v_mov_b32_e32 v106, 0
	v_mov_b32_e32 v107, 0
	v_mov_b32_e32 v108, 0
	v_mov_b32_e32 v109, 0
	v_mov_b32_e32 v110, 0
	v_mov_b32_e32 v111, 0
	v_mov_b32_e32 v112, 0
	v_mov_b32_e32 v113, 0
	v_mov_b32_e32 v114, 0
	v_mov_b32_e32 v115, 0
	v_mov_b32_e32 v116, 0
	v_mov_b32_e32 v117, 0
	v_mov_b32_e32 v118, 0
	v_mov_b32_e32 v119, 0
	v_mov_b32_e32 v120, 0
	v_mov_b32_e32 v121, 0
	v_mov_b32_e32 v122, 0
	v_mov_b32_e32 v123, 0
	v_mov_b32_e32 v124, 0
	v_mov_b32_e32 v125, 0
	v_mov_b32_e32 v126, 0
	v_mov_b32_e32 v127, 0
	s_waitcnt vmcnt(12)
	v_or_b32_e32 v2, v186, v128
	s_waitcnt lgkmcnt(0)
	s_barrier
; #define RAW_BARRIER() do { asm volatile("s_waitcnt lgkmcnt(0)" ::: "memory"); __builtin_amdgcn_s_barrier(); } while (0)
; #define WAIT_VM(n) asm volatile("s_waitcnt vmcnt(" #n ")" ::: "memory")
; template <bool AF32>
; DI void gemm_main(const void* Ap, int lda, const short* Bp, int K, char* smem, f32x16 (&acc)[4][2]) {
;     ...
;   const int lch = (lane & 3) ^ ((lane >> 4) & 3);
;   const short* ga = (const short*)Ap + (size_t)(w * 32 + (lane >> 2)) * lda + lch * 8;
;   const short* gb = Bp + (size_t)(w * 32 + (lane >> 2)) * K + lch * 8;
;   const size_t a16 = (size_t)16 * lda, b16 = (size_t)16 * K;
;   char* lbase = smem + w * 2048;
;     ...
;   const int x = (r >> 2) & 3;
;   const int off0 = ((h ^ x) << 4);
;   const int aoff = (wm * 128 + r) * 64, boff = GBOFF + (wn * 64 + r) * 64;
;   struct Frag { bf16x8 a[4], b0, b1; };
;     ...
;   const int nk = K >> 5;
;   Frag F0, F1;
;   GLDS(0, 0);
;   GLDS(1, 1);
;   GLDS(2, 2);
;   GLDS(3, 3);
;   WAIT_VM(12);
;   RAW_BARRIER();
;   LOADF(F0, 0, 0);
	ds_read_b128 v[130:133], v2 offset:6144
	ds_read_b128 v[142:145], v2 offset:4096
	ds_read_b128 v[146:149], v2 offset:2048
	ds_read_b128 v[150:153], v2
	v_or_b32_e32 v2, v188, v128
	ds_read_b128 v[134:137], v2 offset:18432
	ds_read_b128 v[138:141], v2 offset:16384
	v_lshl_add_u64 v[2:3], s[8:9], 0, v[0:1]
	v_lshlrev_b32_e32 v4, 4, v4
	v_lshl_add_u64 v[0:1], s[6:7], 0, v[0:1]
	v_or_b32_e32 v0, v0, v4
	v_or_b32_e32 v2, v2, v4
	v_lshl_add_u64 v[180:181], s[36:37], 0, v[0:1]
	v_mov_b32_e32 v0, 0
	v_lshl_add_u64 v[178:179], s[18:19], 0, v[2:3]
	s_mov_b64 s[6:7], 0
	s_mov_b32 s8, 0
	v_mov_b32_e32 v1, v0
	v_mov_b32_e32 v2, v0
	v_mov_b32_e32 v3, v0
	v_mov_b32_e32 v4, v0

; DI int my_tid() { int t = threadIdx.x; asm volatile("" : "+v"(t)); return t; }
; #define RAW_BARRIER() do { asm volatile("s_waitcnt lgkmcnt(0)" ::: "memory"); __builtin_amdgcn_s_barrier(); } while (0)
; #define WAIT_VM(n) asm volatile("s_waitcnt vmcnt(" #n ")" ::: "memory")
; template <bool AF32>
; DI void gemm_main(const void* Ap, int lda, const short* Bp, int K, char* smem, f32x16 (&acc)[4][2]) {
;   const int tid = my_tid(), lane = tid & 63, w = tid >> 6, r = lane & 31, h = lane >> 5;
;   const int wm = w >> 2, wn = w & 3;
; #pragma unroll
;   for (int a = 0; a < 4; a++)
; #pragma unroll
;     for (int b = 0; b < 2; b++)
; #pragma unroll
;       for (int i = 0; i < 16; i++) acc[a][b][i] = 0.f;
;   const int lch = (lane & 3) ^ ((lane >> 4) & 3);
;   const short* ga = (const short*)Ap + (size_t)(w * 32 + (lane >> 2)) * lda + lch * 8;
;   const short* gb = Bp + (size_t)(w * 32 + (lane >> 2)) * K + lch * 8;
;   const size_t a16 = (size_t)16 * lda, b16 = (size_t)16 * K;
;   char* lbase = smem + w * 2048;
;     ...
;   const int x = (r >> 2) & 3;
;   const int off0 = ((h ^ x) << 4);
;   const int aoff = (wm * 128 + r) * 64, boff = GBOFF + (wn * 64 + r) * 64;
;   struct Frag { bf16x8 a[4], b0, b1; };
;     ...
;   const int nk = K >> 5;
;   Frag F0, F1;
;   GLDS(0, 0);
;   GLDS(1, 1);
;   GLDS(2, 2);
;   GLDS(3, 3);
;   WAIT_VM(12);
;   RAW_BARRIER();
.LBB0_767:
	s_lshl_b32 s6, s95, 8
	s_ashr_i32 s7, s6, 31
	s_add_u32 s8, s6, s90
	s_addc_u32 s9, s7, 0
	s_lshl_b64 s[8:9], s[8:9], 11
	s_add_u32 s10, s4, s8
	v_mov_b32_e32 v8, v196
	s_addc_u32 s11, s5, s9
	s_ashr_i32 s87, s86, 31
	s_lshl_b64 s[8:9], s[86:87], 19
	s_waitcnt vmcnt(0)
	v_ashrrev_i32_e32 v7, 6, v8
	v_bfe_u32 v0, v8, 2, 4
	v_lshrrev_b32_e32 v10, 4, v8
	v_lshl_or_b32 v0, v7, 5, v0
	s_add_u32 s12, s18, s8
	v_xor_b32_e32 v4, v10, v8
	v_ashrrev_i32_e32 v1, 31, v0
	s_addc_u32 s13, s19, s9
	v_bfe_u32 v9, v8, 5, 1
	v_lshlrev_b64 v[0:1], 11, v[0:1]
	v_lshlrev_b32_e32 v4, 4, v4
	v_lshlrev_b32_e32 v189, 11, v7
	v_lshrrev_b32_e32 v7, 2, v8
	v_lshl_add_u64 v[2:3], s[12:13], 0, v[0:1]
	v_and_b32_e32 v128, 48, v4
	v_lshl_add_u64 v[4:5], s[10:11], 0, v[0:1]
	v_bitop3_b32 v7, v9, v7, 3 bitop3:0x78
	v_and_b32_e32 v6, 31, v8
	v_lshl_add_u64 v[2:3], v[2:3], 0, v[128:129]
	v_lshl_add_u64 v[4:5], v[4:5], 0, v[128:129]
	v_lshlrev_b32_e32 v128, 4, v7
	v_lshrrev_b32_e32 v7, 1, v8
	v_and_or_b32 v6, v7, s65, v6
	v_readfirstlane_b32 s10, v189
	v_or_b32_e32 v9, 0x400, v189
	v_lshlrev_b32_e32 v186, 6, v6
	v_lshlrev_b32_e32 v6, 6, v8
	s_mov_b32 m0, s10
	s_mov_b64 s[12:13], 0x8000
	v_readfirstlane_b32 s10, v9
	v_and_b32_e32 v188, 0x37c0, v6
	global_load_lds_dwordx4 v[2:3], off
	v_lshl_add_u64 v[6:7], v[2:3], 0, s[12:13]
	s_mov_b32 m0, s10
	v_add_u32_e32 v9, 0x4400, v189
	global_load_lds_dwordx4 v[6:7], off
	v_add_u32_e32 v6, 0x4000, v189
	s_lshl_b64 s[6:7], s[6:7], 11
	v_readfirstlane_b32 s10, v6
	s_mov_b32 m0, s10
	v_readfirstlane_b32 s10, v9
	v_add_u32_e32 v9, 0x8000, v189
	global_load_lds_dwordx4 v[4:5], off
	v_lshl_add_u64 v[6:7], v[4:5], 0, s[12:13]
	s_mov_b32 m0, s10
	v_readfirstlane_b32 s10, v9
	v_add_u32_e32 v9, 0x8400, v189
	global_load_lds_dwordx4 v[6:7], off
	v_lshl_add_u64 v[6:7], v[2:3], 0, 64
	s_mov_b32 m0, s10
	v_readfirstlane_b32 s10, v9
	v_add_u32_e32 v9, 0xc000, v189
	global_load_lds_dwordx4 v[6:7], off
	v_lshl_add_u64 v[6:7], v[2:3], 0, s[66:67]
	s_mov_b32 m0, s10
	v_readfirstlane_b32 s10, v9
	v_add_u32_e32 v9, 0xc400, v189
	global_load_lds_dwordx4 v[6:7], off
	v_lshl_add_u64 v[6:7], v[4:5], 0, 64
	s_mov_b32 m0, s10
	v_readfirstlane_b32 s10, v9
	v_add_u32_e32 v9, 0x10000, v189
	global_load_lds_dwordx4 v[6:7], off
	v_lshl_add_u64 v[6:7], v[4:5], 0, s[66:67]
	s_mov_b32 m0, s10
	v_readfirstlane_b32 s10, v9
	v_add_u32_e32 v9, 0x10400, v189
	global_load_lds_dwordx4 v[6:7], off
	v_lshl_add_u64 v[6:7], v[2:3], 0, s[68:69]
	s_mov_b32 m0, s10
	v_readfirstlane_b32 s10, v9
	v_add_u32_e32 v9, 0x14000, v189
	global_load_lds_dwordx4 v[6:7], off
	v_lshl_add_u64 v[6:7], v[2:3], 0, s[70:71]
	s_mov_b32 m0, s10
	v_readfirstlane_b32 s10, v9
	v_add_u32_e32 v9, 0x14400, v189
	global_load_lds_dwordx4 v[6:7], off
	v_lshl_add_u64 v[6:7], v[4:5], 0, s[68:69]
	s_mov_b32 m0, s10
	v_readfirstlane_b32 s10, v9
	v_add_u32_e32 v9, 0x18000, v189
	global_load_lds_dwordx4 v[6:7], off
	v_lshl_add_u64 v[6:7], v[4:5], 0, s[70:71]
	s_mov_b32 m0, s10
	v_readfirstlane_b32 s10, v9
	global_load_lds_dwordx4 v[6:7], off
	v_lshl_add_u64 v[6:7], v[2:3], 0, s[72:73]
	s_mov_b32 m0, s10
	v_lshl_add_u64 v[2:3], v[2:3], 0, s[74:75]
	global_load_lds_dwordx4 v[6:7], off
	v_add_u32_e32 v6, 0x18400, v189
	v_xor_b32_e32 v187, 32, v128
	v_readfirstlane_b32 s10, v6
	v_add_u32_e32 v6, 0x1c000, v189
	s_mov_b32 m0, s10
	v_readfirstlane_b32 s10, v6
	global_load_lds_dwordx4 v[2:3], off
	v_lshl_add_u64 v[2:3], v[4:5], 0, s[72:73]
	s_mov_b32 m0, s10
	s_nop 0
	global_load_lds_dwordx4 v[2:3], off
	v_lshl_add_u64 v[2:3], v[4:5], 0, s[74:75]
	v_add_u32_e32 v4, 0x1c400, v189
	s_nop 0
	v_readfirstlane_b32 s10, v4
	s_mov_b32 m0, s10
	v_bitop3_b32 v4, v10, 3, v8 bitop3:0x48
	global_load_lds_dwordx4 v[2:3], off
	v_mov_b32_e32 v5, 0
	v_mov_b32_e32 v6, 0
	v_mov_b32_e32 v7, 0
	v_mov_b32_e32 v8, 0
	v_mov_b32_e32 v9, 0
	v_mov_b32_e32 v10, 0
	v_mov_b32_e32 v11, 0
	v_mov_b32_e32 v12, 0
	v_mov_b32_e32 v13, 0
	v_mov_b32_e32 v14, 0
	v_mov_b32_e32 v15, 0
	v_mov_b32_e32 v16, 0
	v_mov_b32_e32 v17, 0
	v_mov_b32_e32 v18, 0
	v_mov_b32_e32 v19, 0
	v_mov_b32_e32 v20, 0
	v_mov_b32_e32 v21, 0
	v_mov_b32_e32 v22, 0
	v_mov_b32_e32 v23, 0
	v_mov_b32_e32 v24, 0
	v_mov_b32_e32 v25, 0
	v_mov_b32_e32 v26, 0
	v_mov_b32_e32 v27, 0
	v_mov_b32_e32 v28, 0
	v_mov_b32_e32 v29, 0
	v_mov_b32_e32 v30, 0
	v_mov_b32_e32 v31, 0
	v_mov_b32_e32 v32, 0
	v_mov_b32_e32 v33, 0
	v_mov_b32_e32 v34, 0
	v_mov_b32_e32 v35, 0
	v_mov_b32_e32 v36, 0
	v_mov_b32_e32 v37, 0
	v_mov_b32_e32 v38, 0
	v_mov_b32_e32 v39, 0
	v_mov_b32_e32 v40, 0
	v_mov_b32_e32 v41, 0
	v_mov_b32_e32 v42, 0
	v_mov_b32_e32 v43, 0
	v_mov_b32_e32 v44, 0
	v_mov_b32_e32 v45, 0
	v_mov_b32_e32 v46, 0
	v_mov_b32_e32 v47, 0
	v_mov_b32_e32 v48, 0
	v_mov_b32_e32 v49, 0
	v_mov_b32_e32 v50, 0
	v_mov_b32_e32 v51, 0
	v_mov_b32_e32 v52, 0
	v_mov_b32_e32 v53, 0
	v_mov_b32_e32 v54, 0
	v_mov_b32_e32 v55, 0
	v_mov_b32_e32 v56, 0
	v_mov_b32_e32 v57, 0
	v_mov_b32_e32 v58, 0
	v_mov_b32_e32 v59, 0
	v_mov_b32_e32 v60, 0
	v_mov_b32_e32 v61, 0
	v_mov_b32_e32 v62, 0
	v_mov_b32_e32 v63, 0
	v_mov_b32_e32 v64, 0
	v_mov_b32_e32 v65, 0
	v_mov_b32_e32 v66, 0
	v_mov_b32_e32 v67, 0
	v_mov_b32_e32 v68, 0
	v_mov_b32_e32 v69, 0
	v_mov_b32_e32 v70, 0
	v_mov_b32_e32 v71, 0
	v_mov_b32_e32 v72, 0
	v_mov_b32_e32 v73, 0
	v_mov_b32_e32 v74, 0
	v_mov_b32_e32 v75, 0
	v_mov_b32_e32 v76, 0
	v_mov_b32_e32 v77, 0
	v_mov_b32_e32 v78, 0
	v_mov_b32_e32 v79, 0
	v_mov_b32_e32 v80, 0
	v_mov_b32_e32 v81, 0
	v_mov_b32_e32 v82, 0
	v_mov_b32_e32 v83, 0
	v_mov_b32_e32 v84, 0
	v_mov_b32_e32 v85, 0
	v_mov_b32_e32 v86, 0
	v_mov_b32_e32 v87, 0
	v_mov_b32_e32 v88, 0
	v_mov_b32_e32 v89, 0
	v_mov_b32_e32 v90, 0
	v_mov_b32_e32 v91, 0
	v_mov_b32_e32 v92, 0
	v_mov_b32_e32 v93, 0
	v_mov_b32_e32 v94, 0
	v_mov_b32_e32 v95, 0
	v_mov_b32_e32 v96, 0
	v_mov_b32_e32 v97, 0
	v_mov_b32_e32 v98, 0
	v_mov_b32_e32 v99, 0
	v_mov_b32_e32 v100, 0
	v_mov_b32_e32 v101, 0
	v_mov_b32_e32 v102, 0
	v_mov_b32_e32 v103, 0
	v_mov_b32_e32 v104, 0
	v_mov_b32_e32 v105, 0
	v_mov_b32_e32 v106, 0
	v_mov_b32_e32 v107, 0
	v_mov_b32_e32 v108, 0
	v_mov_b32_e32 v109, 0
	v_mov_b32_e32 v110, 0
	v_mov_b32_e32 v111, 0
	v_mov_b32_e32 v112, 0
	v_mov_b32_e32 v113, 0
	v_mov_b32_e32 v114, 0
	v_mov_b32_e32 v115, 0
	v_mov_b32_e32 v116, 0
	v_mov_b32_e32 v117, 0
	v_mov_b32_e32 v118, 0
	v_mov_b32_e32 v119, 0
	v_mov_b32_e32 v120, 0
	v_mov_b32_e32 v121, 0
	v_mov_b32_e32 v122, 0
	v_mov_b32_e32 v123, 0
	v_mov_b32_e32 v124, 0
	v_mov_b32_e32 v125, 0
	v_mov_b32_e32 v126, 0
	v_mov_b32_e32 v127, 0
	s_waitcnt vmcnt(12)
	v_or_b32_e32 v2, v186, v128
	s_waitcnt lgkmcnt(0)
	s_barrier
; #define RAW_BARRIER() do { asm volatile("s_waitcnt lgkmcnt(0)" ::: "memory"); __builtin_amdgcn_s_barrier(); } while (0)
; #define WAIT_VM(n) asm volatile("s_waitcnt vmcnt(" #n ")" ::: "memory")
; template <bool AF32>
; DI void gemm_main(const void* Ap, int lda, const short* Bp, int K, char* smem, f32x16 (&acc)[4][2]) {
;     ...
;   const int lch = (lane & 3) ^ ((lane >> 4) & 3);
;   const short* ga = (const short*)Ap + (size_t)(w * 32 + (lane >> 2)) * lda + lch * 8;
;   const short* gb = Bp + (size_t)(w * 32 + (lane >> 2)) * K + lch * 8;
;   const size_t a16 = (size_t)16 * lda, b16 = (size_t)16 * K;
;   char* lbase = smem + w * 2048;
;     ...
;   const int x = (r >> 2) & 3;
;   const int off0 = ((h ^ x) << 4);
;   const int aoff = (wm * 128 + r) * 64, boff = GBOFF + (wn * 64 + r) * 64;
;   struct Frag { bf16x8 a[4], b0, b1; };
;     ...
;   const int nk = K >> 5;
;   Frag F0, F1;
;   GLDS(0, 0);
;   GLDS(1, 1);
;   GLDS(2, 2);
;   GLDS(3, 3);
;   WAIT_VM(12);
;   RAW_BARRIER();
;   LOADF(F0, 0, 0);
	ds_read_b128 v[130:133], v2 offset:6144
	ds_read_b128 v[142:145], v2 offset:4096
	ds_read_b128 v[146:149], v2 offset:2048
	ds_read_b128 v[150:153], v2
	v_or_b32_e32 v2, v188, v128
	ds_read_b128 v[134:137], v2 offset:18432
	ds_read_b128 v[138:141], v2 offset:16384
	v_lshl_add_u64 v[2:3], s[8:9], 0, v[0:1]
	v_lshlrev_b32_e32 v4, 4, v4
	v_lshl_add_u64 v[0:1], s[6:7], 0, v[0:1]
	v_or_b32_e32 v0, v0, v4
	v_or_b32_e32 v2, v2, v4
	v_lshl_add_u64 v[180:181], s[16:17], 0, v[0:1]
	v_mov_b32_e32 v0, 0
	v_lshl_add_u64 v[178:179], s[18:19], 0, v[2:3]
	s_mov_b64 s[6:7], 0
	s_mov_b32 s8, 0
	v_mov_b32_e32 v1, v0
	v_mov_b32_e32 v2, v0
	v_mov_b32_e32 v3, v0
	v_mov_b32_e32 v4, v0
